# stack26 + seams 3, 4, 5 as dataflow handshakes (write-through kc/vc, A1, y; per-bg / per-row-panel counters); A2 published in the background by the first workgroup of each XCD to finish P4 (wbl2 + PUB
# speedup vs baseline: 1.0156x; 1.0066x over previous
.LBB0_583:
	s_and_b64 s[16:17], s[14:15], exec
	s_cselect_b32 s17, s7, s9
	s_cselect_b32 s16, s6, s8
	global_load_dword v94, v29, s[16:17]
	global_load_dword v95, v29, s[16:17] offset:2048
	s_add_u32 s16, s16, 0x1000
	s_addc_u32 s17, s17, 0
	global_load_dword v96, v29, s[16:17]
	global_load_dword v97, v29, s[16:17] offset:2048
	s_add_u32 s16, s16, 0x1000
	s_addc_u32 s17, s17, 0
	global_load_dword v98, v29, s[16:17]
	global_load_dword v99, v29, s[16:17] offset:2048
	s_add_u32 s16, s16, 0x1000
	s_addc_u32 s17, s17, 0
	global_load_dword v100, v29, s[16:17]
	global_load_dword v101, v29, s[16:17] offset:2048
	s_add_u32 s16, s16, 0x1000
	s_addc_u32 s17, s17, 0
	global_load_dword v102, v29, s[16:17]
	global_load_dword v103, v29, s[16:17] offset:2048
	s_add_u32 s16, s16, 0x1000
	s_addc_u32 s17, s17, 0
	global_load_dword v104, v29, s[16:17]
	global_load_dword v105, v29, s[16:17] offset:2048
	s_add_u32 s16, s16, 0x1000
	s_addc_u32 s17, s17, 0
	global_load_dword v106, v29, s[16:17]
	global_load_dword v107, v29, s[16:17] offset:2048
	s_add_u32 s16, s16, 0x1000
	s_addc_u32 s17, s17, 0
	global_load_dword v108, v29, s[16:17]
	global_load_dword v109, v29, s[16:17] offset:2048
	s_add_u32 s16, s16, 0x1000
	s_addc_u32 s17, s17, 0
	global_load_dword v110, v29, s[16:17]
	global_load_dword v111, v29, s[16:17] offset:2048
	s_add_u32 s16, s16, 0x1000
	s_addc_u32 s17, s17, 0
	global_load_dword v112, v29, s[16:17]
	global_load_dword v113, v29, s[16:17] offset:2048
	s_add_u32 s16, s16, 0x1000
	s_addc_u32 s17, s17, 0
	global_load_dword v114, v29, s[16:17]
	global_load_dword v115, v29, s[16:17] offset:2048
	s_add_u32 s16, s16, 0x1000
	s_addc_u32 s17, s17, 0
	global_load_dword v116, v29, s[16:17]
	global_load_dword v117, v29, s[16:17] offset:2048
	s_add_u32 s16, s16, 0x1000
	s_addc_u32 s17, s17, 0
	global_load_dword v118, v29, s[16:17]
	global_load_dword v119, v29, s[16:17] offset:2048
	s_add_u32 s16, s16, 0x1000
	s_addc_u32 s17, s17, 0
	global_load_dword v120, v29, s[16:17]
	global_load_dword v121, v29, s[16:17] offset:2048
	s_add_u32 s16, s16, 0x1000
	s_addc_u32 s17, s17, 0
	global_load_dword v122, v29, s[16:17]
	global_load_dword v123, v29, s[16:17] offset:2048
	s_add_u32 s16, s16, 0x1000
	s_addc_u32 s17, s17, 0
	global_load_dword v124, v29, s[16:17]
	global_load_dword v125, v29, s[16:17] offset:2048
	s_add_u32 s16, s16, 0x1000
	s_addc_u32 s17, s17, 0
	global_load_dword v126, v29, s[16:17]
	global_load_dword v127, v29, s[16:17] offset:2048
	s_add_u32 s16, s16, 0x1000
	s_addc_u32 s17, s17, 0
	global_load_dword v128, v29, s[16:17]
	global_load_dword v129, v29, s[16:17] offset:2048
	s_add_u32 s16, s16, 0x1000
	s_addc_u32 s17, s17, 0
	global_load_dword v130, v29, s[16:17]
	global_load_dword v131, v29, s[16:17] offset:2048
	s_add_u32 s16, s16, 0x1000
	s_addc_u32 s17, s17, 0
	global_load_dword v132, v29, s[16:17]
	global_load_dword v133, v29, s[16:17] offset:2048
	s_add_u32 s16, s16, 0x1000
	s_addc_u32 s17, s17, 0
	global_load_dword v134, v29, s[16:17]
	global_load_dword v135, v29, s[16:17] offset:2048
	s_add_u32 s16, s16, 0x1000
	s_addc_u32 s17, s17, 0
	global_load_dword v136, v29, s[16:17]
	global_load_dword v137, v29, s[16:17] offset:2048
	s_add_u32 s16, s16, 0x1000
	s_addc_u32 s17, s17, 0
	global_load_dword v138, v29, s[16:17]
	global_load_dword v139, v29, s[16:17] offset:2048
	s_add_u32 s16, s16, 0x1000
	s_addc_u32 s17, s17, 0
	global_load_dword v140, v29, s[16:17]
	global_load_dword v141, v29, s[16:17] offset:2048
	s_add_u32 s16, s16, 0x1000
	s_addc_u32 s17, s17, 0
	global_load_dword v142, v29, s[16:17]
	global_load_dword v143, v29, s[16:17] offset:2048
	s_add_u32 s16, s16, 0x1000
	s_addc_u32 s17, s17, 0
	global_load_dword v144, v29, s[16:17]
	global_load_dword v145, v29, s[16:17] offset:2048
	s_add_u32 s16, s16, 0x1000
	s_addc_u32 s17, s17, 0
	global_load_dword v146, v29, s[16:17]
	global_load_dword v147, v29, s[16:17] offset:2048
	s_add_u32 s16, s16, 0x1000
	s_addc_u32 s17, s17, 0
	global_load_dword v148, v29, s[16:17]
	global_load_dword v149, v29, s[16:17] offset:2048
	s_add_u32 s16, s16, 0x1000
	s_addc_u32 s17, s17, 0
	global_load_dword v150, v29, s[16:17]
	global_load_dword v151, v29, s[16:17] offset:2048
	s_add_u32 s16, s16, 0x1000
	s_addc_u32 s17, s17, 0
	global_load_dword v152, v29, s[16:17]
	global_load_dword v153, v29, s[16:17] offset:2048
	s_add_u32 s16, s16, 0x1000
	s_addc_u32 s17, s17, 0
	s_waitcnt lgkmcnt(0)
	s_barrier
	ds_read_b32 v30, v28
	ds_read_b32 v31, v28 offset:256
	ds_read_b32 v32, v28 offset:512
	ds_read_b32 v33, v28 offset:768
	ds_read_b32 v34, v28 offset:1024
	ds_read_b32 v35, v28 offset:1280
	ds_read_b32 v36, v28 offset:1536
	ds_read_b32 v37, v28 offset:1792
	ds_read_b32 v38, v28 offset:2048
	ds_read_b32 v39, v28 offset:2304
	ds_read_b32 v40, v28 offset:2560
	ds_read_b32 v41, v28 offset:2816
	ds_read_b32 v42, v28 offset:3072
	ds_read_b32 v43, v28 offset:3328
	ds_read_b32 v44, v28 offset:3584
	ds_read_b32 v45, v28 offset:3840
	ds_read_b32 v46, v28 offset:4096
	ds_read_b32 v47, v28 offset:4352
	ds_read_b32 v48, v28 offset:4608
	ds_read_b32 v49, v28 offset:4864
	ds_read_b32 v50, v28 offset:5120
	ds_read_b32 v51, v28 offset:5376
	ds_read_b32 v52, v28 offset:5632
	ds_read_b32 v53, v28 offset:5888
	ds_read_b32 v54, v28 offset:6144
	ds_read_b32 v55, v28 offset:6400
	ds_read_b32 v56, v28 offset:6656
	ds_read_b32 v57, v28 offset:6912
	ds_read_b32 v58, v28 offset:7168
	ds_read_b32 v59, v28 offset:7424
	ds_read_b32 v60, v28 offset:7680
	ds_read_b32 v61, v28 offset:7936
	s_waitcnt vmcnt(59) lgkmcnt(15)
	v_mfma_f32_16x16x4_f32 v[62:65], v30, v94, 0
	s_waitcnt vmcnt(58) lgkmcnt(15)
	v_mfma_f32_16x16x4_f32 v[66:69], v31, v95, 0
	s_waitcnt vmcnt(57) lgkmcnt(15)
	v_mfma_f32_16x16x4_f32 v[70:73], v32, v96, 0
	s_waitcnt vmcnt(56) lgkmcnt(15)
	v_mfma_f32_16x16x4_f32 v[74:77], v33, v97, 0
	global_load_dword v154, v29, s[16:17]
	global_load_dword v155, v29, s[16:17] offset:2048
	s_add_u32 s16, s16, 0x1000
	s_addc_u32 s17, s17, 0
	global_load_dword v156, v29, s[16:17]
	global_load_dword v157, v29, s[16:17] offset:2048
	s_waitcnt vmcnt(59) lgkmcnt(15)
	v_mfma_f32_16x16x4_f32 v[62:65], v34, v98, v[62:65]
	s_waitcnt vmcnt(58) lgkmcnt(15)
	v_mfma_f32_16x16x4_f32 v[66:69], v35, v99, v[66:69]
	s_waitcnt vmcnt(57) lgkmcnt(15)
	v_mfma_f32_16x16x4_f32 v[70:73], v36, v100, v[70:73]
	s_waitcnt vmcnt(56) lgkmcnt(15)
	v_mfma_f32_16x16x4_f32 v[74:77], v37, v101, v[74:77]
	s_waitcnt vmcnt(55) lgkmcnt(15)
	v_mfma_f32_16x16x4_f32 v[62:65], v38, v102, v[62:65]
	s_waitcnt vmcnt(54) lgkmcnt(15)
	v_mfma_f32_16x16x4_f32 v[66:69], v39, v103, v[66:69]
	s_waitcnt vmcnt(53) lgkmcnt(15)
	v_mfma_f32_16x16x4_f32 v[70:73], v40, v104, v[70:73]
	s_waitcnt vmcnt(52) lgkmcnt(15)
	v_mfma_f32_16x16x4_f32 v[74:77], v41, v105, v[74:77]
	s_waitcnt vmcnt(51) lgkmcnt(15)
	v_mfma_f32_16x16x4_f32 v[62:65], v42, v106, v[62:65]
	s_waitcnt vmcnt(50) lgkmcnt(15)
	v_mfma_f32_16x16x4_f32 v[66:69], v43, v107, v[66:69]
	s_waitcnt vmcnt(49) lgkmcnt(15)
	v_mfma_f32_16x16x4_f32 v[70:73], v44, v108, v[70:73]
	s_waitcnt vmcnt(48) lgkmcnt(15)
	v_mfma_f32_16x16x4_f32 v[74:77], v45, v109, v[74:77]
	ds_read_b32 v30, v28 offset:8192
	ds_read_b32 v31, v28 offset:8448
	ds_read_b32 v32, v28 offset:8704
	ds_read_b32 v33, v28 offset:8960
	ds_read_b32 v34, v28 offset:9216
	ds_read_b32 v35, v28 offset:9472
	ds_read_b32 v36, v28 offset:9728
	ds_read_b32 v37, v28 offset:9984
	ds_read_b32 v38, v28 offset:10240
	ds_read_b32 v39, v28 offset:10496
	ds_read_b32 v40, v28 offset:10752
	ds_read_b32 v41, v28 offset:11008
	ds_read_b32 v42, v28 offset:11264
	ds_read_b32 v43, v28 offset:11520
	ds_read_b32 v44, v28 offset:11776
	ds_read_b32 v45, v28 offset:12032
	s_waitcnt vmcnt(47) lgkmcnt(15)
	v_mfma_f32_16x16x4_f32 v[62:65], v46, v110, v[62:65]
	s_waitcnt vmcnt(46) lgkmcnt(15)
	v_mfma_f32_16x16x4_f32 v[66:69], v47, v111, v[66:69]
	s_waitcnt vmcnt(45) lgkmcnt(15)
	v_mfma_f32_16x16x4_f32 v[70:73], v48, v112, v[70:73]
	s_waitcnt vmcnt(44) lgkmcnt(15)
	v_mfma_f32_16x16x4_f32 v[74:77], v49, v113, v[74:77]
	s_waitcnt vmcnt(43) lgkmcnt(15)
	v_mfma_f32_16x16x4_f32 v[62:65], v50, v114, v[62:65]
	s_waitcnt vmcnt(42) lgkmcnt(15)
	v_mfma_f32_16x16x4_f32 v[66:69], v51, v115, v[66:69]
	s_waitcnt vmcnt(41) lgkmcnt(15)
	v_mfma_f32_16x16x4_f32 v[70:73], v52, v116, v[70:73]
	s_waitcnt vmcnt(40) lgkmcnt(15)
	v_mfma_f32_16x16x4_f32 v[74:77], v53, v117, v[74:77]
	s_waitcnt vmcnt(39) lgkmcnt(15)
	v_mfma_f32_16x16x4_f32 v[62:65], v54, v118, v[62:65]
	s_waitcnt vmcnt(38) lgkmcnt(15)
	v_mfma_f32_16x16x4_f32 v[66:69], v55, v119, v[66:69]
	s_waitcnt vmcnt(37) lgkmcnt(15)
	v_mfma_f32_16x16x4_f32 v[70:73], v56, v120, v[70:73]
	s_waitcnt vmcnt(36) lgkmcnt(15)
	v_mfma_f32_16x16x4_f32 v[74:77], v57, v121, v[74:77]
	s_waitcnt vmcnt(35) lgkmcnt(15)
	v_mfma_f32_16x16x4_f32 v[62:65], v58, v122, v[62:65]
	s_waitcnt vmcnt(34) lgkmcnt(15)
	v_mfma_f32_16x16x4_f32 v[66:69], v59, v123, v[66:69]
	s_waitcnt vmcnt(33) lgkmcnt(15)
	v_mfma_f32_16x16x4_f32 v[70:73], v60, v124, v[70:73]
	s_waitcnt vmcnt(32) lgkmcnt(15)
	v_mfma_f32_16x16x4_f32 v[74:77], v61, v125, v[74:77]
	ds_read_b32 v46, v28 offset:12288
	ds_read_b32 v47, v28 offset:12544
	ds_read_b32 v48, v28 offset:12800
	ds_read_b32 v49, v28 offset:13056
	ds_read_b32 v50, v28 offset:13312
	ds_read_b32 v51, v28 offset:13568
	ds_read_b32 v52, v28 offset:13824
	ds_read_b32 v53, v28 offset:14080
	ds_read_b32 v54, v28 offset:14336
	ds_read_b32 v55, v28 offset:14592
	ds_read_b32 v56, v28 offset:14848
	ds_read_b32 v57, v28 offset:15104
	ds_read_b32 v58, v28 offset:15360
	ds_read_b32 v59, v28 offset:15616
	ds_read_b32 v60, v28 offset:15872
	ds_read_b32 v61, v28 offset:16128
	s_waitcnt vmcnt(31) lgkmcnt(15)
	v_mfma_f32_16x16x4_f32 v[62:65], v30, v126, v[62:65]
	s_waitcnt vmcnt(30) lgkmcnt(15)
	v_mfma_f32_16x16x4_f32 v[66:69], v31, v127, v[66:69]
	s_waitcnt vmcnt(29) lgkmcnt(15)
	v_mfma_f32_16x16x4_f32 v[70:73], v32, v128, v[70:73]
	s_waitcnt vmcnt(28) lgkmcnt(15)
	v_mfma_f32_16x16x4_f32 v[74:77], v33, v129, v[74:77]
	s_waitcnt vmcnt(27) lgkmcnt(15)
	v_mfma_f32_16x16x4_f32 v[62:65], v34, v130, v[62:65]
	s_waitcnt vmcnt(26) lgkmcnt(15)
	v_mfma_f32_16x16x4_f32 v[66:69], v35, v131, v[66:69]
	s_waitcnt vmcnt(25) lgkmcnt(15)
	v_mfma_f32_16x16x4_f32 v[70:73], v36, v132, v[70:73]
	s_waitcnt vmcnt(24) lgkmcnt(15)
	v_mfma_f32_16x16x4_f32 v[74:77], v37, v133, v[74:77]
	s_waitcnt vmcnt(23) lgkmcnt(15)
	v_mfma_f32_16x16x4_f32 v[62:65], v38, v134, v[62:65]
	s_waitcnt vmcnt(22) lgkmcnt(15)
	v_mfma_f32_16x16x4_f32 v[66:69], v39, v135, v[66:69]
	s_waitcnt vmcnt(21) lgkmcnt(15)
	v_mfma_f32_16x16x4_f32 v[70:73], v40, v136, v[70:73]
	s_waitcnt vmcnt(20) lgkmcnt(15)
	v_mfma_f32_16x16x4_f32 v[74:77], v41, v137, v[74:77]
	s_waitcnt vmcnt(19) lgkmcnt(15)
	v_mfma_f32_16x16x4_f32 v[62:65], v42, v138, v[62:65]
	s_waitcnt vmcnt(18) lgkmcnt(15)
	v_mfma_f32_16x16x4_f32 v[66:69], v43, v139, v[66:69]
	s_waitcnt vmcnt(17) lgkmcnt(15)
	v_mfma_f32_16x16x4_f32 v[70:73], v44, v140, v[70:73]
	s_waitcnt vmcnt(16) lgkmcnt(15)
	v_mfma_f32_16x16x4_f32 v[74:77], v45, v141, v[74:77]
	s_waitcnt vmcnt(15) lgkmcnt(15)
	v_mfma_f32_16x16x4_f32 v[62:65], v46, v142, v[62:65]
	s_waitcnt vmcnt(14) lgkmcnt(14)
	v_mfma_f32_16x16x4_f32 v[66:69], v47, v143, v[66:69]
	s_waitcnt vmcnt(13) lgkmcnt(13)
	v_mfma_f32_16x16x4_f32 v[70:73], v48, v144, v[70:73]
	s_waitcnt vmcnt(12) lgkmcnt(12)
	v_mfma_f32_16x16x4_f32 v[74:77], v49, v145, v[74:77]
	s_waitcnt vmcnt(11) lgkmcnt(11)
	v_mfma_f32_16x16x4_f32 v[62:65], v50, v146, v[62:65]
	s_waitcnt vmcnt(10) lgkmcnt(10)
	v_mfma_f32_16x16x4_f32 v[66:69], v51, v147, v[66:69]
	s_waitcnt vmcnt(9) lgkmcnt(9)
	v_mfma_f32_16x16x4_f32 v[70:73], v52, v148, v[70:73]
	s_waitcnt vmcnt(8) lgkmcnt(8)
	v_mfma_f32_16x16x4_f32 v[74:77], v53, v149, v[74:77]
	s_waitcnt vmcnt(7) lgkmcnt(7)
	v_mfma_f32_16x16x4_f32 v[62:65], v54, v150, v[62:65]
	s_waitcnt vmcnt(6) lgkmcnt(6)
	v_mfma_f32_16x16x4_f32 v[66:69], v55, v151, v[66:69]
	s_waitcnt vmcnt(5) lgkmcnt(5)
	v_mfma_f32_16x16x4_f32 v[70:73], v56, v152, v[70:73]
	s_waitcnt vmcnt(4) lgkmcnt(4)
	v_mfma_f32_16x16x4_f32 v[74:77], v57, v153, v[74:77]
	s_waitcnt vmcnt(3) lgkmcnt(3)
	v_mfma_f32_16x16x4_f32 v[62:65], v58, v154, v[62:65]
	s_waitcnt vmcnt(2) lgkmcnt(2)
	v_mfma_f32_16x16x4_f32 v[66:69], v59, v155, v[66:69]
	s_waitcnt vmcnt(1) lgkmcnt(1)
	v_mfma_f32_16x16x4_f32 v[70:73], v60, v156, v[70:73]
	s_waitcnt vmcnt(0) lgkmcnt(0)
	v_mfma_f32_16x16x4_f32 v[74:77], v61, v157, v[74:77]
	s_nop 15
	s_nop 3
	v_add_f32_e32 v12, v62, v66
	v_add_f32_e32 v4, v70, v74
	s_nop 0
	v_add_f32_e32 v12, v12, v4
	v_add_f32_e32 v13, v63, v67
	v_add_f32_e32 v4, v71, v75
	s_nop 0
	v_add_f32_e32 v13, v13, v4
	v_add_f32_e32 v10, v64, v68
	v_add_f32_e32 v4, v72, v76
	s_nop 0
	v_add_f32_e32 v10, v10, v4
	v_add_f32_e32 v11, v65, v69
	v_add_f32_e32 v4, v73, v77
	s_nop 0
	v_add_f32_e32 v11, v11, v4
	s_and_b64 s[14:15], s[14:15], exec
	s_cselect_b32 s10, s22, 0x1cdb3400
	s_add_u32 s14, s76, s10
	v_add_u32_e32 v30, s27, v14
	s_addc_u32 s15, s77, 0
	v_add_lshl_u32 v4, v30, s28, 8
	v_lshl_add_u64 v[8:9], s[14:15], 0, v[4:5]
	v_lshlrev_b32_e32 v4, 1, v2
	v_lshl_add_u64 v[8:9], v[8:9], 0, v[4:5]
	v_cvt_pk_bf16_f32 v4, v12, s0
	v_cmp_gt_u32_e32 vcc, s0, v30
	s_add_i32 s26, s26, s79
	s_cmpk_gt_i32 s26, 0xff
	v_cndmask_b32_e32 v4, 0, v4, vcc
	global_store_short v[8:9], v4, off sc1
	v_cvt_pk_bf16_f32 v4, v13, s0
	v_cmp_gt_u32_e32 vcc, s23, v30
	s_nop 1
	v_cndmask_b32_e32 v4, 0, v4, vcc
	global_store_short v[8:9], v4, off offset:256 sc1
	v_cvt_pk_bf16_f32 v4, v10, s0
	v_cmp_gt_u32_e32 vcc, s24, v30
	s_nop 1
	v_cndmask_b32_e32 v4, 0, v4, vcc
	global_store_short v[8:9], v4, off offset:512 sc1
	v_cvt_pk_bf16_f32 v4, v11, s0
	v_cmp_gt_u32_e32 vcc, s25, v30
	s_nop 1
	v_cndmask_b32_e32 v4, 0, v4, vcc
	global_store_short v[8:9], v4, off offset:768 sc1
	s_barrier
	s_cbranch_scc0 .LBB0_573
.LBB0_586:
	s_cmp_gt_i32 s89, 4
	s_cselect_b64 s[4:5], -1, 0
	s_and_b64 s[0:1], s[2:3], s[4:5]
	s_andn2_b64 vcc, exec, s[0:1]
	s_cbranch_vccnz .LBB0_640
	s_waitcnt vmcnt(0)
	s_waitcnt vmcnt(0)
	s_barrier
	s_and_saveexec_b64 s[2:3], s[84:85]
	s_cbranch_execz .LBB0_639
	s_cmp_lg_u32 s79, 0x100
	s_cbranch_scc1 .Ldf3_full
	s_lshr_b32 s0, s78, 3
	s_and_b32 s0, s0, 15
	s_lshl_b32 s0, s0, 8
	s_add_i32 s0, s0, 0xa000
	v_mov_b32_e32 v2, s0
	v_mov_b32_e32 v3, 1
	global_atomic_add v2, v3, s[76:77]
	s_lshl_b32 s0, s82, 8
	s_add_i32 s0, s0, 0xb000
	v_mov_b32_e32 v4, s0
	global_atomic_add v4, v3, s[76:77]
	s_and_b32 s0, s78, 7
	s_lshl_b32 s0, s0, 5
	s_lshr_b32 s1, s78, 3
	s_add_i32 s0, s0, s1
	s_lshr_b32 s0, s0, 4
	s_lshl_b32 s0, s0, 8
	s_add_i32 s0, s0, 0xa000
	v_mov_b32_e32 v2, s0
	s_mov_b32 s101, 0
.Ldf3_l:
	global_load_dword v4, v2, s[76:77] sc1
	s_waitcnt vmcnt(0)
	v_readfirstlane_b32 s0, v4
	s_cmp_ge_u32 s0, 16
	s_cbranch_scc1 .Ldf3_g
	s_sleep 1
	s_add_i32 s101, s101, 1
	s_cmp_lt_u32 s101, 0x100000
	s_cbranch_scc1 .Ldf3_l

.LBB0_706:
	s_cmp_gt_i32 s89, 5
	v_readlane_b32 s0, v246, 0
	s_cselect_b64 s[2:3], -1, 0
	v_readlane_b32 s1, v246, 1
	s_and_b64 s[0:1], s[0:1], s[2:3]
	s_andn2_b64 vcc, exec, s[0:1]
	s_cbranch_vccnz .LBB0_760
	s_waitcnt vmcnt(0)
	s_waitcnt vmcnt(0)
	s_barrier
	s_and_saveexec_b64 s[4:5], s[84:85]
	s_cbranch_execz .LBB0_759
	s_cmp_lg_u32 s79, 0x100
	s_cbranch_scc1 .Ldf4_full
	s_and_b32 s0, s78, 7
	s_lshl_b32 s0, s0, 5
	s_lshr_b32 s1, s78, 3
	s_add_i32 s0, s0, s1
	s_lshr_b32 s1, s0, 6
	s_lshl_b32 s1, s1, 3
	s_and_b32 s6, s0, 15
	s_lshr_b32 s7, s6, 2
	s_add_i32 s7, s7, s1
	s_sub_i32 s6, 31, s6
	s_lshr_b32 s6, s6, 2
	s_add_i32 s6, s6, s1
	s_and_b32 s98, s0, 7
	s_add_i32 s98, s98, s1
	s_lshl_b32 s6, s6, 8
	s_add_i32 s6, s6, 0xe000
	s_lshl_b32 s7, s7, 8
	s_add_i32 s7, s7, 0xe000
	s_lshl_b32 s98, s98, 8
	s_add_i32 s98, s98, 0xe000
	s_lshl_b32 s99, s82, 8
	s_add_i32 s99, s99, 0xb080
	v_mov_b32_e32 v5, s99
	v_mov_b32_e32 v3, 1
	global_atomic_add v6, v5, v3, s[76:77] sc0
	v_mov_b32_e32 v2, s6
	global_atomic_add v2, v3, s[76:77]
	v_mov_b32_e32 v4, s7
	global_atomic_add v4, v3, s[76:77]
	s_waitcnt vmcnt(0)
	v_readfirstlane_b32 s99, v6
	s_cmp_lg_u32 s99, 0
	s_cbranch_scc1 .Ldf4_nopub
	v_mov_b32_e32 v5, 0x23e20
	ds_read_b32 v6, v5
	s_waitcnt lgkmcnt(0)
	s_nop 0
	v_readfirstlane_b32 s100, v6
	s_lshl_b32 s99, s82, 8
	s_add_i32 s99, s99, 0xb000
	v_mov_b32_e32 v5, s99
	s_mov_b32 s101, 0
.Ldf4p_l:
	global_load_dword v6, v5, s[76:77] sc1
	s_waitcnt vmcnt(0)
	v_readfirstlane_b32 s99, v6
	s_cmp_ge_u32 s99, s100
	s_cbranch_scc1 .Ldf4p_g
	s_sleep 1
	s_add_i32 s101, s101, 1
	s_cmp_lt_u32 s101, 0x100000
	s_cbranch_scc1 .Ldf4p_l
.Ldf4p_g:
	buffer_wbl2 sc1
	s_waitcnt vmcnt(0)
	v_mov_b32_e32 v5, 0xa080
	global_atomic_add v5, v3, s[76:77]
.Ldf4_nopub:
	v_mov_b32_e32 v5, 0x23e24
	ds_read_b32 v6, v5
	s_waitcnt lgkmcnt(0)
	s_nop 0
	v_readfirstlane_b32 s100, v6
	v_mov_b32_e32 v2, s98
	v_mov_b32_e32 v5, 0xa080
	s_mov_b32 s101, 0
.Ldf4_l:
	global_load_dword v4, v2, s[76:77] sc1
	global_load_dword v6, v5, s[76:77] sc1
	s_waitcnt vmcnt(0)
	v_readfirstlane_b32 s0, v4
	v_readfirstlane_b32 s1, v6
	s_cmp_ge_u32 s0, 16
	s_cselect_b32 s0, 1, 0
	s_cmp_ge_u32 s1, s100
	s_cselect_b32 s1, 1, 0
	s_and_b32 s0, s0, s1
	s_cmp_lg_u32 s0, 0
	s_cbranch_scc1 .Ldf4_g
	s_sleep 1
	s_add_i32 s101, s101, 1
	s_cmp_lt_u32 s101, 0x100000
	s_cbranch_scc1 .Ldf4_l
